# back-edge rotation, second form: loop counter/pointer/exit test parked at the end of the last load part (no issue slots inserted between MFMAs); loop head issues the fragment reads first
# speedup vs baseline: 1.0082x; 1.0082x over previous
.LBB0_278:
	s_add_i32 s73, 0, 0x10000
	v_add_u32_e32 v2, s73, v191
	s_add_i32 s76, 0, 0x14000
	ds_read_b128 v[132:135], v2
	ds_read_b128 v[136:139], v2 offset:1024
	ds_read_b128 v[140:143], v2 offset:2048
	ds_read_b128 v[144:147], v2 offset:3072
	v_add_u32_e32 v2, s76, v191
	ds_read_b128 v[148:151], v2
	ds_read_b128 v[152:155], v2 offset:1024
	ds_read_b128 v[156:159], v2 offset:2048
	ds_read_b128 v[160:163], v2 offset:3072
	v_lshl_add_u64 v[188:189], s[6:7], 0, v[174:175]
	s_add_i32 m0, s47, 0xc000
	ds_read_b128 v[176:179], v197
	ds_read_b128 v[180:183], v197 offset:1024
	ds_read_b128 v[184:187], v197 offset:2048
	ds_read_b128 v[192:195], v197 offset:3072
	ds_read_b128 v[198:201], v197 offset:4096
	ds_read_b128 v[202:205], v197 offset:5120
	ds_read_b128 v[206:209], v197 offset:6144
	ds_read_b128 v[220:223], v197 offset:7168
	global_load_lds_dwordx4 v[188:189], off
	v_lshl_add_u64 v[188:189], s[6:7], 0, v[172:173]
	s_add_i32 m0, s47, 0xe000
	s_nop 0
	global_load_lds_dwordx4 v[188:189], off
	s_add_u32 s8, s6, 0xfff80080
	s_addc_u32 s9, s7, -1
	s_cmp_eq_u32 s72, 28
	s_cselect_b32 s39, s43, s9
	s_cselect_b32 s38, s52, s8
	s_cselect_b32 s9, s45, s67
	s_cselect_b32 s8, s65, s66
	s_waitcnt vmcnt(8)
	s_waitcnt lgkmcnt(0)
	s_barrier
	s_setprio 1
	s_waitcnt lgkmcnt(0)
	v_mfma_f32_16x16x32_bf16 v[124:127], v[132:135], v[176:179], v[124:127]
	v_mfma_f32_16x16x32_bf16 v[128:131], v[140:143], v[176:179], v[128:131]
	v_mfma_f32_16x16x32_bf16 v[108:111], v[132:135], v[184:187], v[108:111]
	v_mfma_f32_16x16x32_bf16 v[112:115], v[140:143], v[184:187], v[112:115]
	v_mfma_f32_16x16x32_bf16 v[92:95], v[132:135], v[198:201], v[92:95]
	v_mfma_f32_16x16x32_bf16 v[96:99], v[140:143], v[198:201], v[96:99]
	v_mfma_f32_16x16x32_bf16 v[76:79], v[132:135], v[206:209], v[76:79]
	v_mfma_f32_16x16x32_bf16 v[80:83], v[140:143], v[206:209], v[80:83]
	v_mfma_f32_16x16x32_bf16 v[124:127], v[136:139], v[180:183], v[124:127]
	v_mfma_f32_16x16x32_bf16 v[128:131], v[144:147], v[180:183], v[128:131]
	v_mfma_f32_16x16x32_bf16 v[108:111], v[136:139], v[192:195], v[108:111]
	v_mfma_f32_16x16x32_bf16 v[112:115], v[144:147], v[192:195], v[112:115]
	v_mfma_f32_16x16x32_bf16 v[92:95], v[136:139], v[202:205], v[92:95]
	v_mfma_f32_16x16x32_bf16 v[96:99], v[144:147], v[202:205], v[96:99]
	v_mfma_f32_16x16x32_bf16 v[76:79], v[136:139], v[220:223], v[76:79]
	v_mfma_f32_16x16x32_bf16 v[80:83], v[144:147], v[220:223], v[80:83]
	s_setprio 0
	s_setprio 1
	v_mfma_f32_16x16x32_bf16 v[116:119], v[148:151], v[176:179], v[116:119]
	v_mfma_f32_16x16x32_bf16 v[120:123], v[156:159], v[176:179], v[120:123]
	v_mfma_f32_16x16x32_bf16 v[100:103], v[148:151], v[184:187], v[100:103]
	v_mfma_f32_16x16x32_bf16 v[104:107], v[156:159], v[184:187], v[104:107]
	v_mfma_f32_16x16x32_bf16 v[84:87], v[148:151], v[198:201], v[84:87]
	v_mfma_f32_16x16x32_bf16 v[88:91], v[156:159], v[198:201], v[88:91]
	v_mfma_f32_16x16x32_bf16 v[68:71], v[148:151], v[206:209], v[68:71]
	v_mfma_f32_16x16x32_bf16 v[72:75], v[156:159], v[206:209], v[72:75]
	v_mfma_f32_16x16x32_bf16 v[116:119], v[152:155], v[180:183], v[116:119]
	v_mfma_f32_16x16x32_bf16 v[120:123], v[160:163], v[180:183], v[120:123]
	v_mfma_f32_16x16x32_bf16 v[100:103], v[152:155], v[192:195], v[100:103]
	v_mfma_f32_16x16x32_bf16 v[104:107], v[160:163], v[192:195], v[104:107]
	v_mfma_f32_16x16x32_bf16 v[84:87], v[152:155], v[202:205], v[84:87]
	v_mfma_f32_16x16x32_bf16 v[88:91], v[160:163], v[202:205], v[88:91]
	v_mfma_f32_16x16x32_bf16 v[68:71], v[152:155], v[220:223], v[68:71]
	v_mfma_f32_16x16x32_bf16 v[72:75], v[160:163], v[220:223], v[72:75]
	s_setprio 0
	s_barrier
	s_add_i32 s73, s73, s46
	v_lshl_add_u64 v[188:189], s[8:9], 0, v[168:169]
	s_mov_b32 m0, s73
	ds_read_b128 v[176:179], v197 offset:16384
	ds_read_b128 v[180:183], v197 offset:17408
	ds_read_b128 v[184:187], v197 offset:18432
	ds_read_b128 v[192:195], v197 offset:19456
	ds_read_b128 v[198:201], v197 offset:20480
	ds_read_b128 v[202:205], v197 offset:21504
	ds_read_b128 v[206:209], v197 offset:22528
	ds_read_b128 v[220:223], v197 offset:23552
	global_load_lds_dwordx4 v[188:189], off
	s_add_i32 m0, s73, 0x2000
	s_add_u32 s74, s8, 0x80000
	v_lshl_add_u64 v[210:211], s[8:9], 0, v[164:165]
	s_addc_u32 s75, s9, 0
	s_add_i32 s73, s76, s46
	global_load_lds_dwordx4 v[210:211], off
	v_lshl_add_u64 v[216:217], s[74:75], 0, v[168:169]
	s_mov_b32 m0, s73
	v_lshl_add_u64 v[224:225], s[38:39], 0, v[166:167]
	global_load_lds_dwordx4 v[216:217], off
	v_lshl_add_u64 v[216:217], s[74:75], 0, v[164:165]
	s_add_i32 m0, s73, 0x2000
	s_mov_b64 s[76:77], 0x80
	global_load_lds_dwordx4 v[216:217], off
	v_lshl_add_u64 v[216:217], s[38:39], 0, v[170:171]
	s_mov_b32 m0, s47
	s_nop 0
	global_load_lds_dwordx4 v[216:217], off
	s_mov_b32 m0, s48
	s_nop 0
	global_load_lds_dwordx4 v[224:225], off
	s_waitcnt vmcnt(8)
	s_waitcnt lgkmcnt(0)
	s_barrier
	s_setprio 1
	s_waitcnt lgkmcnt(0)
	v_mfma_f32_16x16x32_bf16 v[60:63], v[132:135], v[176:179], v[60:63]
	v_mfma_f32_16x16x32_bf16 v[64:67], v[140:143], v[176:179], v[64:67]
	v_mfma_f32_16x16x32_bf16 v[44:47], v[132:135], v[184:187], v[44:47]
	v_mfma_f32_16x16x32_bf16 v[48:51], v[140:143], v[184:187], v[48:51]
	v_mfma_f32_16x16x32_bf16 v[28:31], v[132:135], v[198:201], v[28:31]
	v_mfma_f32_16x16x32_bf16 v[32:35], v[140:143], v[198:201], v[32:35]
	v_mfma_f32_16x16x32_bf16 v[12:15], v[132:135], v[206:209], v[12:15]
	v_mfma_f32_16x16x32_bf16 v[16:19], v[140:143], v[206:209], v[16:19]
	v_mfma_f32_16x16x32_bf16 v[60:63], v[136:139], v[180:183], v[60:63]
	v_mfma_f32_16x16x32_bf16 v[64:67], v[144:147], v[180:183], v[64:67]
	v_mfma_f32_16x16x32_bf16 v[44:47], v[136:139], v[192:195], v[44:47]
	v_mfma_f32_16x16x32_bf16 v[48:51], v[144:147], v[192:195], v[48:51]
	v_mfma_f32_16x16x32_bf16 v[28:31], v[136:139], v[202:205], v[28:31]
	v_mfma_f32_16x16x32_bf16 v[32:35], v[144:147], v[202:205], v[32:35]
	v_mfma_f32_16x16x32_bf16 v[12:15], v[136:139], v[220:223], v[12:15]
	v_mfma_f32_16x16x32_bf16 v[16:19], v[144:147], v[220:223], v[16:19]
	s_setprio 0
	s_setprio 1
	v_mfma_f32_16x16x32_bf16 v[52:55], v[148:151], v[176:179], v[52:55]
	v_mfma_f32_16x16x32_bf16 v[56:59], v[156:159], v[176:179], v[56:59]
	v_mfma_f32_16x16x32_bf16 v[36:39], v[148:151], v[184:187], v[36:39]
	v_mfma_f32_16x16x32_bf16 v[40:43], v[156:159], v[184:187], v[40:43]
	v_mfma_f32_16x16x32_bf16 v[20:23], v[148:151], v[198:201], v[20:23]
	v_mfma_f32_16x16x32_bf16 v[24:27], v[156:159], v[198:201], v[24:27]
	v_mfma_f32_16x16x32_bf16 v[4:7], v[148:151], v[206:209], v[4:7]
	v_mfma_f32_16x16x32_bf16 v[8:11], v[156:159], v[206:209], v[8:11]
	v_mfma_f32_16x16x32_bf16 v[52:55], v[152:155], v[180:183], v[52:55]
	v_mfma_f32_16x16x32_bf16 v[56:59], v[160:163], v[180:183], v[56:59]
	v_mfma_f32_16x16x32_bf16 v[36:39], v[152:155], v[192:195], v[36:39]
	v_mfma_f32_16x16x32_bf16 v[40:43], v[160:163], v[192:195], v[40:43]
	v_mfma_f32_16x16x32_bf16 v[20:23], v[152:155], v[202:205], v[20:23]
	v_mfma_f32_16x16x32_bf16 v[24:27], v[160:163], v[202:205], v[24:27]
	v_mfma_f32_16x16x32_bf16 v[4:7], v[152:155], v[220:223], v[4:7]
	v_mfma_f32_16x16x32_bf16 v[8:11], v[160:163], v[220:223], v[8:11]
	s_setprio 0
	s_barrier
	s_add_i32 s73, 0, 0x18000
	v_add_u32_e32 v2, s73, v191
	s_add_i32 s74, 0, 0x1c000
	ds_read_b128 v[132:135], v2
	ds_read_b128 v[136:139], v2 offset:1024
	ds_read_b128 v[140:143], v2 offset:2048
	ds_read_b128 v[144:147], v2 offset:3072
	v_add_u32_e32 v2, s74, v191
	ds_read_b128 v[148:151], v2
	ds_read_b128 v[152:155], v2 offset:1024
	ds_read_b128 v[156:159], v2 offset:2048
	ds_read_b128 v[160:163], v2 offset:3072
	s_add_u32 s38, s38, 0x80000
	s_addc_u32 s39, s39, 0
	s_mov_b32 m0, s49
	v_lshl_add_u64 v[226:227], s[38:39], 0, v[170:171]
	ds_read_b128 v[176:179], v197 offset:32768
	ds_read_b128 v[180:183], v197 offset:33792
	ds_read_b128 v[184:187], v197 offset:34816
	ds_read_b128 v[192:195], v197 offset:35840
	ds_read_b128 v[198:201], v197 offset:36864
	ds_read_b128 v[202:205], v197 offset:37888
	ds_read_b128 v[206:209], v197 offset:38912
	ds_read_b128 v[220:223], v197 offset:39936
	global_load_lds_dwordx4 v[226:227], off
	v_lshl_add_u64 v[226:227], s[38:39], 0, v[166:167]
	s_mov_b32 m0, s54
	s_nop 0
	global_load_lds_dwordx4 v[226:227], off
	s_waitcnt vmcnt(8)
	s_waitcnt lgkmcnt(0)
	s_barrier
	s_setprio 1
	s_waitcnt lgkmcnt(0)
	v_mfma_f32_16x16x32_bf16 v[124:127], v[132:135], v[176:179], v[124:127]
	v_mfma_f32_16x16x32_bf16 v[128:131], v[140:143], v[176:179], v[128:131]
	v_mfma_f32_16x16x32_bf16 v[108:111], v[132:135], v[184:187], v[108:111]
	v_mfma_f32_16x16x32_bf16 v[112:115], v[140:143], v[184:187], v[112:115]
	v_mfma_f32_16x16x32_bf16 v[92:95], v[132:135], v[198:201], v[92:95]
	v_mfma_f32_16x16x32_bf16 v[96:99], v[140:143], v[198:201], v[96:99]
	v_mfma_f32_16x16x32_bf16 v[76:79], v[132:135], v[206:209], v[76:79]
	v_mfma_f32_16x16x32_bf16 v[80:83], v[140:143], v[206:209], v[80:83]
	v_mfma_f32_16x16x32_bf16 v[124:127], v[136:139], v[180:183], v[124:127]
	v_mfma_f32_16x16x32_bf16 v[128:131], v[144:147], v[180:183], v[128:131]
	v_mfma_f32_16x16x32_bf16 v[108:111], v[136:139], v[192:195], v[108:111]
	v_mfma_f32_16x16x32_bf16 v[112:115], v[144:147], v[192:195], v[112:115]
	v_mfma_f32_16x16x32_bf16 v[92:95], v[136:139], v[202:205], v[92:95]
	v_mfma_f32_16x16x32_bf16 v[96:99], v[144:147], v[202:205], v[96:99]
	v_mfma_f32_16x16x32_bf16 v[76:79], v[136:139], v[220:223], v[76:79]
	v_mfma_f32_16x16x32_bf16 v[80:83], v[144:147], v[220:223], v[80:83]
	s_setprio 0
	s_setprio 1
	v_mfma_f32_16x16x32_bf16 v[116:119], v[148:151], v[176:179], v[116:119]
	v_mfma_f32_16x16x32_bf16 v[120:123], v[156:159], v[176:179], v[120:123]
	v_mfma_f32_16x16x32_bf16 v[100:103], v[148:151], v[184:187], v[100:103]
	v_mfma_f32_16x16x32_bf16 v[104:107], v[156:159], v[184:187], v[104:107]
	v_mfma_f32_16x16x32_bf16 v[84:87], v[148:151], v[198:201], v[84:87]
	v_mfma_f32_16x16x32_bf16 v[88:91], v[156:159], v[198:201], v[88:91]
	v_mfma_f32_16x16x32_bf16 v[68:71], v[148:151], v[206:209], v[68:71]
	v_mfma_f32_16x16x32_bf16 v[72:75], v[156:159], v[206:209], v[72:75]
	v_mfma_f32_16x16x32_bf16 v[116:119], v[152:155], v[180:183], v[116:119]
	v_mfma_f32_16x16x32_bf16 v[120:123], v[160:163], v[180:183], v[120:123]
	v_mfma_f32_16x16x32_bf16 v[100:103], v[152:155], v[192:195], v[100:103]
	v_mfma_f32_16x16x32_bf16 v[104:107], v[160:163], v[192:195], v[104:107]
	v_mfma_f32_16x16x32_bf16 v[84:87], v[152:155], v[202:205], v[84:87]
	v_mfma_f32_16x16x32_bf16 v[88:91], v[160:163], v[202:205], v[88:91]
	v_mfma_f32_16x16x32_bf16 v[68:71], v[152:155], v[220:223], v[68:71]
	v_mfma_f32_16x16x32_bf16 v[72:75], v[160:163], v[220:223], v[72:75]
	s_setprio 0
	s_barrier
	s_add_i32 s38, s73, s46
	v_lshl_add_u64 v[188:189], v[188:189], 0, s[76:77]
	s_mov_b32 m0, s38
	ds_read_b128 v[176:179], v197 offset:49152
	ds_read_b128 v[180:183], v197 offset:50176
	ds_read_b128 v[184:187], v197 offset:51200
	ds_read_b128 v[192:195], v197 offset:52224
	ds_read_b128 v[198:201], v197 offset:53248
	ds_read_b128 v[202:205], v197 offset:54272
	ds_read_b128 v[206:209], v197 offset:55296
	ds_read_b128 v[220:223], v197 offset:56320
	global_load_lds_dwordx4 v[188:189], off
	s_add_i32 m0, s38, 0x2000
	s_add_u32 s8, s8, 0x80080
	v_lshl_add_u64 v[188:189], v[210:211], 0, s[76:77]
	s_addc_u32 s9, s9, 0
	s_add_i32 s38, s74, s46
	global_load_lds_dwordx4 v[188:189], off
	v_lshl_add_u64 v[188:189], s[8:9], 0, v[168:169]
	s_mov_b32 m0, s38
	s_nop 0
	global_load_lds_dwordx4 v[188:189], off
	v_lshl_add_u64 v[188:189], s[8:9], 0, v[164:165]
	s_add_i32 m0, s38, 0x2000
	s_nop 0
	global_load_lds_dwordx4 v[188:189], off
	v_lshl_add_u64 v[188:189], v[216:217], 0, s[76:77]
	s_mov_b32 m0, s59
	s_nop 0
	global_load_lds_dwordx4 v[188:189], off
	v_lshl_add_u64 v[188:189], v[224:225], 0, s[76:77]
	s_mov_b32 m0, s60
	s_nop 0
	global_load_lds_dwordx4 v[188:189], off
	s_add_i32 s72, s72, 2
	s_add_u32 s66, s66, 0x100
	s_addc_u32 s67, s67, 0
	s_add_u32 s6, s6, 0x100
	s_addc_u32 s7, s7, 0
	s_cmp_gt_u32 s72, 29
	s_waitcnt vmcnt(8)
	s_waitcnt lgkmcnt(0)
	s_barrier
	s_setprio 1
	s_waitcnt lgkmcnt(0)
	v_mfma_f32_16x16x32_bf16 v[60:63], v[132:135], v[176:179], v[60:63]
	v_mfma_f32_16x16x32_bf16 v[64:67], v[140:143], v[176:179], v[64:67]
	v_mfma_f32_16x16x32_bf16 v[44:47], v[132:135], v[184:187], v[44:47]
	v_mfma_f32_16x16x32_bf16 v[48:51], v[140:143], v[184:187], v[48:51]
	v_mfma_f32_16x16x32_bf16 v[28:31], v[132:135], v[198:201], v[28:31]
	v_mfma_f32_16x16x32_bf16 v[32:35], v[140:143], v[198:201], v[32:35]
	v_mfma_f32_16x16x32_bf16 v[12:15], v[132:135], v[206:209], v[12:15]
	v_mfma_f32_16x16x32_bf16 v[16:19], v[140:143], v[206:209], v[16:19]
	v_mfma_f32_16x16x32_bf16 v[60:63], v[136:139], v[180:183], v[60:63]
	v_mfma_f32_16x16x32_bf16 v[64:67], v[144:147], v[180:183], v[64:67]
	v_mfma_f32_16x16x32_bf16 v[44:47], v[136:139], v[192:195], v[44:47]
	v_mfma_f32_16x16x32_bf16 v[48:51], v[144:147], v[192:195], v[48:51]
	v_mfma_f32_16x16x32_bf16 v[28:31], v[136:139], v[202:205], v[28:31]
	v_mfma_f32_16x16x32_bf16 v[32:35], v[144:147], v[202:205], v[32:35]
	v_mfma_f32_16x16x32_bf16 v[12:15], v[136:139], v[220:223], v[12:15]
	v_mfma_f32_16x16x32_bf16 v[16:19], v[144:147], v[220:223], v[16:19]
	s_setprio 0
	s_setprio 1
	v_mfma_f32_16x16x32_bf16 v[52:55], v[148:151], v[176:179], v[52:55]
	v_mfma_f32_16x16x32_bf16 v[56:59], v[156:159], v[176:179], v[56:59]
	v_mfma_f32_16x16x32_bf16 v[36:39], v[148:151], v[184:187], v[36:39]
	v_mfma_f32_16x16x32_bf16 v[40:43], v[156:159], v[184:187], v[40:43]
	v_mfma_f32_16x16x32_bf16 v[20:23], v[148:151], v[198:201], v[20:23]
	v_mfma_f32_16x16x32_bf16 v[24:27], v[156:159], v[198:201], v[24:27]
	v_mfma_f32_16x16x32_bf16 v[4:7], v[148:151], v[206:209], v[4:7]
	v_mfma_f32_16x16x32_bf16 v[8:11], v[156:159], v[206:209], v[8:11]
	v_mfma_f32_16x16x32_bf16 v[52:55], v[152:155], v[180:183], v[52:55]
	v_mfma_f32_16x16x32_bf16 v[56:59], v[160:163], v[180:183], v[56:59]
	v_mfma_f32_16x16x32_bf16 v[36:39], v[152:155], v[192:195], v[36:39]
	v_mfma_f32_16x16x32_bf16 v[40:43], v[160:163], v[192:195], v[40:43]
	v_mfma_f32_16x16x32_bf16 v[20:23], v[152:155], v[202:205], v[20:23]
	v_mfma_f32_16x16x32_bf16 v[24:27], v[160:163], v[202:205], v[24:27]
	v_mfma_f32_16x16x32_bf16 v[4:7], v[152:155], v[220:223], v[4:7]
	v_mfma_f32_16x16x32_bf16 v[8:11], v[160:163], v[220:223], v[8:11]
	s_setprio 0
	s_barrier
	s_cbranch_scc0 .LBB0_278
	s_and_b64 vcc, exec, s[18:19]
	s_cbranch_vccz .LBB0_281
	s_barrier

.LBB0_1229:
	s_add_i32 s56, 0, 0x10000
	v_add_u32_e32 v2, s56, v216
	s_add_i32 s58, 0, 0x14000
	ds_read_b128 v[132:135], v2
	ds_read_b128 v[136:139], v2 offset:1024
	ds_read_b128 v[140:143], v2 offset:2048
	ds_read_b128 v[144:147], v2 offset:3072
	v_add_u32_e32 v2, s58, v216
	ds_read_b128 v[148:151], v2
	ds_read_b128 v[152:155], v2 offset:1024
	ds_read_b128 v[156:159], v2 offset:2048
	ds_read_b128 v[160:163], v2 offset:3072
	v_lshl_add_u64 v[208:209], s[18:19], 0, v[198:199]
	s_add_i32 m0, s29, 0xc000
	ds_read_b128 v[164:167], v217
	ds_read_b128 v[168:171], v217 offset:1024
	ds_read_b128 v[172:175], v217 offset:2048
	ds_read_b128 v[176:179], v217 offset:3072
	ds_read_b128 v[180:183], v217 offset:4096
	ds_read_b128 v[184:187], v217 offset:5120
	ds_read_b128 v[200:203], v217 offset:6144
	ds_read_b128 v[204:207], v217 offset:7168
	global_load_lds_dwordx4 v[208:209], off
	v_lshl_add_u64 v[208:209], s[18:19], 0, v[196:197]
	s_add_i32 m0, s29, 0xe000
	s_nop 0
	global_load_lds_dwordx4 v[208:209], off
	s_add_u32 s20, s18, 0xfff80080
	s_addc_u32 s21, s19, -1
	s_cmp_eq_u32 s52, 28
	s_cselect_b32 s23, s13, s21
	s_cselect_b32 s22, s46, s20
	s_cselect_b32 s21, s11, s49
	s_cselect_b32 s20, s47, s48
	s_waitcnt vmcnt(8)
	s_waitcnt lgkmcnt(0)
	s_barrier
	s_setprio 1
	s_waitcnt lgkmcnt(0)
	v_mfma_f32_16x16x32_bf16 v[128:131], v[132:135], v[164:167], v[128:131]
	v_mfma_f32_16x16x32_bf16 v[124:127], v[140:143], v[164:167], v[124:127]
	v_mfma_f32_16x16x32_bf16 v[112:115], v[132:135], v[172:175], v[112:115]
	v_mfma_f32_16x16x32_bf16 v[108:111], v[140:143], v[172:175], v[108:111]
	v_mfma_f32_16x16x32_bf16 v[96:99], v[132:135], v[180:183], v[96:99]
	v_mfma_f32_16x16x32_bf16 v[92:95], v[140:143], v[180:183], v[92:95]
	v_mfma_f32_16x16x32_bf16 v[80:83], v[132:135], v[200:203], v[80:83]
	v_mfma_f32_16x16x32_bf16 v[76:79], v[140:143], v[200:203], v[76:79]
	v_mfma_f32_16x16x32_bf16 v[128:131], v[136:139], v[168:171], v[128:131]
	v_mfma_f32_16x16x32_bf16 v[124:127], v[144:147], v[168:171], v[124:127]
	v_mfma_f32_16x16x32_bf16 v[112:115], v[136:139], v[176:179], v[112:115]
	v_mfma_f32_16x16x32_bf16 v[108:111], v[144:147], v[176:179], v[108:111]
	v_mfma_f32_16x16x32_bf16 v[96:99], v[136:139], v[184:187], v[96:99]
	v_mfma_f32_16x16x32_bf16 v[92:95], v[144:147], v[184:187], v[92:95]
	v_mfma_f32_16x16x32_bf16 v[80:83], v[136:139], v[204:207], v[80:83]
	v_mfma_f32_16x16x32_bf16 v[76:79], v[144:147], v[204:207], v[76:79]
	s_setprio 0
	s_setprio 1
	v_mfma_f32_16x16x32_bf16 v[120:123], v[148:151], v[164:167], v[120:123]
	v_mfma_f32_16x16x32_bf16 v[116:119], v[156:159], v[164:167], v[116:119]
	v_mfma_f32_16x16x32_bf16 v[104:107], v[148:151], v[172:175], v[104:107]
	v_mfma_f32_16x16x32_bf16 v[100:103], v[156:159], v[172:175], v[100:103]
	v_mfma_f32_16x16x32_bf16 v[88:91], v[148:151], v[180:183], v[88:91]
	v_mfma_f32_16x16x32_bf16 v[84:87], v[156:159], v[180:183], v[84:87]
	v_mfma_f32_16x16x32_bf16 v[72:75], v[148:151], v[200:203], v[72:75]
	v_mfma_f32_16x16x32_bf16 v[68:71], v[156:159], v[200:203], v[68:71]
	v_mfma_f32_16x16x32_bf16 v[120:123], v[152:155], v[168:171], v[120:123]
	v_mfma_f32_16x16x32_bf16 v[116:119], v[160:163], v[168:171], v[116:119]
	v_mfma_f32_16x16x32_bf16 v[104:107], v[152:155], v[176:179], v[104:107]
	v_mfma_f32_16x16x32_bf16 v[100:103], v[160:163], v[176:179], v[100:103]
	v_mfma_f32_16x16x32_bf16 v[88:91], v[152:155], v[184:187], v[88:91]
	v_mfma_f32_16x16x32_bf16 v[84:87], v[160:163], v[184:187], v[84:87]
	v_mfma_f32_16x16x32_bf16 v[72:75], v[152:155], v[204:207], v[72:75]
	v_mfma_f32_16x16x32_bf16 v[68:71], v[160:163], v[204:207], v[68:71]
	s_setprio 0
	s_barrier
	s_add_i32 s56, s56, s28
	v_lshl_add_u64 v[208:209], s[20:21], 0, v[192:193]
	s_mov_b32 m0, s56
	ds_read_b128 v[164:167], v217 offset:16384
	ds_read_b128 v[168:171], v217 offset:17408
	ds_read_b128 v[172:175], v217 offset:18432
	ds_read_b128 v[176:179], v217 offset:19456
	ds_read_b128 v[180:183], v217 offset:20480
	ds_read_b128 v[184:187], v217 offset:21504
	ds_read_b128 v[200:203], v217 offset:22528
	ds_read_b128 v[204:207], v217 offset:23552
	global_load_lds_dwordx4 v[208:209], off
	s_add_i32 m0, s56, 0x2000
	s_add_u32 s56, s20, 0x80000
	v_lshl_add_u64 v[210:211], s[20:21], 0, v[188:189]
	s_addc_u32 s57, s21, 0
	s_add_i32 s58, s58, s28
	global_load_lds_dwordx4 v[210:211], off
	v_lshl_add_u64 v[220:221], s[56:57], 0, v[192:193]
	s_mov_b32 m0, s58
	v_lshl_add_u64 v[222:223], s[22:23], 0, v[190:191]
	global_load_lds_dwordx4 v[220:221], off
	v_lshl_add_u64 v[220:221], s[56:57], 0, v[188:189]
	s_add_i32 m0, s58, 0x2000
	s_nop 0
	global_load_lds_dwordx4 v[220:221], off
	v_lshl_add_u64 v[220:221], s[22:23], 0, v[194:195]
	s_mov_b32 m0, s29
	s_nop 0
	global_load_lds_dwordx4 v[220:221], off
	s_mov_b32 m0, s30
	s_nop 0
	global_load_lds_dwordx4 v[222:223], off
	s_waitcnt vmcnt(8)
	s_waitcnt lgkmcnt(0)
	s_barrier
	s_setprio 1
	s_waitcnt lgkmcnt(0)
	v_mfma_f32_16x16x32_bf16 v[64:67], v[132:135], v[164:167], v[64:67]
	v_mfma_f32_16x16x32_bf16 v[60:63], v[140:143], v[164:167], v[60:63]
	v_mfma_f32_16x16x32_bf16 v[48:51], v[132:135], v[172:175], v[48:51]
	v_mfma_f32_16x16x32_bf16 v[44:47], v[140:143], v[172:175], v[44:47]
	v_mfma_f32_16x16x32_bf16 v[32:35], v[132:135], v[180:183], v[32:35]
	v_mfma_f32_16x16x32_bf16 v[28:31], v[140:143], v[180:183], v[28:31]
	v_mfma_f32_16x16x32_bf16 v[16:19], v[132:135], v[200:203], v[16:19]
	v_mfma_f32_16x16x32_bf16 v[12:15], v[140:143], v[200:203], v[12:15]
	v_mfma_f32_16x16x32_bf16 v[64:67], v[136:139], v[168:171], v[64:67]
	v_mfma_f32_16x16x32_bf16 v[60:63], v[144:147], v[168:171], v[60:63]
	v_mfma_f32_16x16x32_bf16 v[48:51], v[136:139], v[176:179], v[48:51]
	v_mfma_f32_16x16x32_bf16 v[44:47], v[144:147], v[176:179], v[44:47]
	v_mfma_f32_16x16x32_bf16 v[32:35], v[136:139], v[184:187], v[32:35]
	v_mfma_f32_16x16x32_bf16 v[28:31], v[144:147], v[184:187], v[28:31]
	v_mfma_f32_16x16x32_bf16 v[16:19], v[136:139], v[204:207], v[16:19]
	v_mfma_f32_16x16x32_bf16 v[12:15], v[144:147], v[204:207], v[12:15]
	s_setprio 0
	s_setprio 1
	v_mfma_f32_16x16x32_bf16 v[56:59], v[148:151], v[164:167], v[56:59]
	v_mfma_f32_16x16x32_bf16 v[52:55], v[156:159], v[164:167], v[52:55]
	v_mfma_f32_16x16x32_bf16 v[40:43], v[148:151], v[172:175], v[40:43]
	v_mfma_f32_16x16x32_bf16 v[36:39], v[156:159], v[172:175], v[36:39]
	v_mfma_f32_16x16x32_bf16 v[24:27], v[148:151], v[180:183], v[24:27]
	v_mfma_f32_16x16x32_bf16 v[20:23], v[156:159], v[180:183], v[20:23]
	v_mfma_f32_16x16x32_bf16 v[8:11], v[148:151], v[200:203], v[8:11]
	v_mfma_f32_16x16x32_bf16 v[4:7], v[156:159], v[200:203], v[4:7]
	v_mfma_f32_16x16x32_bf16 v[56:59], v[152:155], v[168:171], v[56:59]
	v_mfma_f32_16x16x32_bf16 v[52:55], v[160:163], v[168:171], v[52:55]
	v_mfma_f32_16x16x32_bf16 v[40:43], v[152:155], v[176:179], v[40:43]
	v_mfma_f32_16x16x32_bf16 v[36:39], v[160:163], v[176:179], v[36:39]
	v_mfma_f32_16x16x32_bf16 v[24:27], v[152:155], v[184:187], v[24:27]
	v_mfma_f32_16x16x32_bf16 v[20:23], v[160:163], v[184:187], v[20:23]
	v_mfma_f32_16x16x32_bf16 v[8:11], v[152:155], v[204:207], v[8:11]
	v_mfma_f32_16x16x32_bf16 v[4:7], v[160:163], v[204:207], v[4:7]
	s_setprio 0
	s_barrier
	s_add_i32 s56, 0, 0x18000
	v_add_u32_e32 v2, s56, v216
	s_add_i32 s57, 0, 0x1c000
	ds_read_b128 v[132:135], v2
	ds_read_b128 v[136:139], v2 offset:1024
	ds_read_b128 v[140:143], v2 offset:2048
	ds_read_b128 v[144:147], v2 offset:3072
	v_add_u32_e32 v2, s57, v216
	ds_read_b128 v[148:151], v2
	ds_read_b128 v[152:155], v2 offset:1024
	ds_read_b128 v[156:159], v2 offset:2048
	ds_read_b128 v[160:163], v2 offset:3072
	s_add_u32 s22, s22, 0x80000
	s_addc_u32 s23, s23, 0
	s_mov_b32 m0, s31
	v_lshl_add_u64 v[224:225], s[22:23], 0, v[194:195]
	ds_read_b128 v[164:167], v217 offset:32768
	ds_read_b128 v[168:171], v217 offset:33792
	ds_read_b128 v[172:175], v217 offset:34816
	ds_read_b128 v[176:179], v217 offset:35840
	ds_read_b128 v[180:183], v217 offset:36864
	ds_read_b128 v[184:187], v217 offset:37888
	ds_read_b128 v[200:203], v217 offset:38912
	ds_read_b128 v[204:207], v217 offset:39936
	global_load_lds_dwordx4 v[224:225], off
	v_lshl_add_u64 v[224:225], s[22:23], 0, v[190:191]
	s_mov_b32 m0, s34
	s_nop 0
	global_load_lds_dwordx4 v[224:225], off
	s_waitcnt vmcnt(8)
	s_waitcnt lgkmcnt(0)
	s_barrier
	s_setprio 1
	s_waitcnt lgkmcnt(0)
	v_mfma_f32_16x16x32_bf16 v[128:131], v[132:135], v[164:167], v[128:131]
	v_mfma_f32_16x16x32_bf16 v[124:127], v[140:143], v[164:167], v[124:127]
	v_mfma_f32_16x16x32_bf16 v[112:115], v[132:135], v[172:175], v[112:115]
	v_mfma_f32_16x16x32_bf16 v[108:111], v[140:143], v[172:175], v[108:111]
	v_mfma_f32_16x16x32_bf16 v[96:99], v[132:135], v[180:183], v[96:99]
	v_mfma_f32_16x16x32_bf16 v[92:95], v[140:143], v[180:183], v[92:95]
	v_mfma_f32_16x16x32_bf16 v[80:83], v[132:135], v[200:203], v[80:83]
	v_mfma_f32_16x16x32_bf16 v[76:79], v[140:143], v[200:203], v[76:79]
	v_mfma_f32_16x16x32_bf16 v[128:131], v[136:139], v[168:171], v[128:131]
	v_mfma_f32_16x16x32_bf16 v[124:127], v[144:147], v[168:171], v[124:127]
	v_mfma_f32_16x16x32_bf16 v[112:115], v[136:139], v[176:179], v[112:115]
	v_mfma_f32_16x16x32_bf16 v[108:111], v[144:147], v[176:179], v[108:111]
	v_mfma_f32_16x16x32_bf16 v[96:99], v[136:139], v[184:187], v[96:99]
	v_mfma_f32_16x16x32_bf16 v[92:95], v[144:147], v[184:187], v[92:95]
	v_mfma_f32_16x16x32_bf16 v[80:83], v[136:139], v[204:207], v[80:83]
	v_mfma_f32_16x16x32_bf16 v[76:79], v[144:147], v[204:207], v[76:79]
	s_setprio 0
	s_setprio 1
	v_mfma_f32_16x16x32_bf16 v[120:123], v[148:151], v[164:167], v[120:123]
	v_mfma_f32_16x16x32_bf16 v[116:119], v[156:159], v[164:167], v[116:119]
	v_mfma_f32_16x16x32_bf16 v[104:107], v[148:151], v[172:175], v[104:107]
	v_mfma_f32_16x16x32_bf16 v[100:103], v[156:159], v[172:175], v[100:103]
	v_mfma_f32_16x16x32_bf16 v[88:91], v[148:151], v[180:183], v[88:91]
	v_mfma_f32_16x16x32_bf16 v[84:87], v[156:159], v[180:183], v[84:87]
	v_mfma_f32_16x16x32_bf16 v[72:75], v[148:151], v[200:203], v[72:75]
	v_mfma_f32_16x16x32_bf16 v[68:71], v[156:159], v[200:203], v[68:71]
	v_mfma_f32_16x16x32_bf16 v[120:123], v[152:155], v[168:171], v[120:123]
	v_mfma_f32_16x16x32_bf16 v[116:119], v[160:163], v[168:171], v[116:119]
	v_mfma_f32_16x16x32_bf16 v[104:107], v[152:155], v[176:179], v[104:107]
	v_mfma_f32_16x16x32_bf16 v[100:103], v[160:163], v[176:179], v[100:103]
	v_mfma_f32_16x16x32_bf16 v[88:91], v[152:155], v[184:187], v[88:91]
	v_mfma_f32_16x16x32_bf16 v[84:87], v[160:163], v[184:187], v[84:87]
	v_mfma_f32_16x16x32_bf16 v[72:75], v[152:155], v[204:207], v[72:75]
	v_mfma_f32_16x16x32_bf16 v[68:71], v[160:163], v[204:207], v[68:71]
	s_setprio 0
	s_barrier
	s_add_i32 s22, s56, s28
	v_lshl_add_u64 v[208:209], v[208:209], 0, s[76:77]
	s_mov_b32 m0, s22
	ds_read_b128 v[164:167], v217 offset:49152
	ds_read_b128 v[168:171], v217 offset:50176
	ds_read_b128 v[172:175], v217 offset:51200
	ds_read_b128 v[176:179], v217 offset:52224
	ds_read_b128 v[180:183], v217 offset:53248
	ds_read_b128 v[184:187], v217 offset:54272
	ds_read_b128 v[200:203], v217 offset:55296
	ds_read_b128 v[204:207], v217 offset:56320
	global_load_lds_dwordx4 v[208:209], off
	s_add_i32 m0, s22, 0x2000
	s_add_u32 s20, s20, 0x80080
	v_lshl_add_u64 v[208:209], v[210:211], 0, s[76:77]
	s_addc_u32 s21, s21, 0
	s_add_i32 s22, s57, s28
	global_load_lds_dwordx4 v[208:209], off
	v_lshl_add_u64 v[208:209], s[20:21], 0, v[192:193]
	s_mov_b32 m0, s22
	s_nop 0
	global_load_lds_dwordx4 v[208:209], off
	v_lshl_add_u64 v[208:209], s[20:21], 0, v[188:189]
	s_add_i32 m0, s22, 0x2000
	s_nop 0
	global_load_lds_dwordx4 v[208:209], off
	v_lshl_add_u64 v[208:209], v[220:221], 0, s[76:77]
	s_mov_b32 m0, s38
	s_nop 0
	global_load_lds_dwordx4 v[208:209], off
	v_lshl_add_u64 v[208:209], v[222:223], 0, s[76:77]
	s_mov_b32 m0, s39
	s_nop 0
	global_load_lds_dwordx4 v[208:209], off
	s_add_i32 s52, s52, 2
	s_add_u32 s48, s48, 0x100
	s_addc_u32 s49, s49, 0
	s_add_u32 s18, s18, 0x100
	s_addc_u32 s19, s19, 0
	s_cmp_gt_u32 s52, 29
	s_waitcnt vmcnt(8)
	s_waitcnt lgkmcnt(0)
	s_barrier
	s_setprio 1
	s_waitcnt lgkmcnt(0)
	v_mfma_f32_16x16x32_bf16 v[64:67], v[132:135], v[164:167], v[64:67]
	v_mfma_f32_16x16x32_bf16 v[60:63], v[140:143], v[164:167], v[60:63]
	v_mfma_f32_16x16x32_bf16 v[48:51], v[132:135], v[172:175], v[48:51]
	v_mfma_f32_16x16x32_bf16 v[44:47], v[140:143], v[172:175], v[44:47]
	v_mfma_f32_16x16x32_bf16 v[32:35], v[132:135], v[180:183], v[32:35]
	v_mfma_f32_16x16x32_bf16 v[28:31], v[140:143], v[180:183], v[28:31]
	v_mfma_f32_16x16x32_bf16 v[16:19], v[132:135], v[200:203], v[16:19]
	v_mfma_f32_16x16x32_bf16 v[12:15], v[140:143], v[200:203], v[12:15]
	v_mfma_f32_16x16x32_bf16 v[64:67], v[136:139], v[168:171], v[64:67]
	v_mfma_f32_16x16x32_bf16 v[60:63], v[144:147], v[168:171], v[60:63]
	v_mfma_f32_16x16x32_bf16 v[48:51], v[136:139], v[176:179], v[48:51]
	v_mfma_f32_16x16x32_bf16 v[44:47], v[144:147], v[176:179], v[44:47]
	v_mfma_f32_16x16x32_bf16 v[32:35], v[136:139], v[184:187], v[32:35]
	v_mfma_f32_16x16x32_bf16 v[28:31], v[144:147], v[184:187], v[28:31]
	v_mfma_f32_16x16x32_bf16 v[16:19], v[136:139], v[204:207], v[16:19]
	v_mfma_f32_16x16x32_bf16 v[12:15], v[144:147], v[204:207], v[12:15]
	s_setprio 0
	s_setprio 1
	v_mfma_f32_16x16x32_bf16 v[56:59], v[148:151], v[164:167], v[56:59]
	v_mfma_f32_16x16x32_bf16 v[52:55], v[156:159], v[164:167], v[52:55]
	v_mfma_f32_16x16x32_bf16 v[40:43], v[148:151], v[172:175], v[40:43]
	v_mfma_f32_16x16x32_bf16 v[36:39], v[156:159], v[172:175], v[36:39]
	v_mfma_f32_16x16x32_bf16 v[24:27], v[148:151], v[180:183], v[24:27]
	v_mfma_f32_16x16x32_bf16 v[20:23], v[156:159], v[180:183], v[20:23]
	v_mfma_f32_16x16x32_bf16 v[8:11], v[148:151], v[200:203], v[8:11]
	v_mfma_f32_16x16x32_bf16 v[4:7], v[156:159], v[200:203], v[4:7]
	v_mfma_f32_16x16x32_bf16 v[56:59], v[152:155], v[168:171], v[56:59]
	v_mfma_f32_16x16x32_bf16 v[52:55], v[160:163], v[168:171], v[52:55]
	v_mfma_f32_16x16x32_bf16 v[40:43], v[152:155], v[176:179], v[40:43]
	v_mfma_f32_16x16x32_bf16 v[36:39], v[160:163], v[176:179], v[36:39]
	v_mfma_f32_16x16x32_bf16 v[24:27], v[152:155], v[184:187], v[24:27]
	v_mfma_f32_16x16x32_bf16 v[20:23], v[160:163], v[184:187], v[20:23]
	v_mfma_f32_16x16x32_bf16 v[8:11], v[152:155], v[204:207], v[8:11]
	v_mfma_f32_16x16x32_bf16 v[4:7], v[160:163], v[204:207], v[4:7]
	s_setprio 0
	s_barrier
	s_cbranch_scc0 .LBB0_1229
	s_and_b64 vcc, exec, s[8:9]
	s_cbranch_vccz .LBB0_1232
	s_barrier

.LBB0_1336:
	s_add_i32 s17, 0, 0x10000
	v_add_u32_e32 v2, s17, v220
	s_add_i32 s41, 0, 0x14000
	ds_read_b128 v[28:31], v2
	ds_read_b128 v[32:35], v2 offset:1024
	ds_read_b128 v[36:39], v2 offset:2048
	ds_read_b128 v[40:43], v2 offset:3072
	v_add_u32_e32 v2, s41, v220
	ds_read_b128 v[44:47], v2
	ds_read_b128 v[48:51], v2 offset:1024
	ds_read_b128 v[52:55], v2 offset:2048
	ds_read_b128 v[56:59], v2 offset:3072
	v_lshl_add_u64 v[196:197], s[8:9], 0, v[232:233]
	s_add_i32 m0, s58, 0xc000
	ds_read_b128 v[92:95], v216
	ds_read_b128 v[96:99], v216 offset:1024
	ds_read_b128 v[100:103], v216 offset:2048
	ds_read_b128 v[104:107], v216 offset:3072
	ds_read_b128 v[108:111], v216 offset:4096
	ds_read_b128 v[112:115], v216 offset:5120
	ds_read_b128 v[116:119], v216 offset:6144
	ds_read_b128 v[120:123], v216 offset:7168
	global_load_lds_dwordx4 v[196:197], off
	v_lshl_add_u64 v[196:197], s[8:9], 0, v[230:231]
	s_add_i32 m0, s58, 0xe000
	s_nop 0
	global_load_lds_dwordx4 v[196:197], off
	s_add_u32 s10, s8, 0xfff80080
	s_addc_u32 s11, s9, -1
	s_cmp_eq_u32 s16, 28
	s_cselect_b32 s15, s18, s11
	s_cselect_b32 s14, s19, s10
	s_cselect_b32 s11, s22, s40
	s_cselect_b32 s10, s23, s39
	s_waitcnt vmcnt(8)
	s_waitcnt lgkmcnt(0)
	s_barrier
	s_setprio 1
	s_waitcnt lgkmcnt(0)
	v_mfma_f32_16x16x32_bf16 v[192:195], v[28:31], v[92:95], v[192:195]
	v_mfma_f32_16x16x32_bf16 v[160:163], v[36:39], v[92:95], v[160:163]
	v_mfma_f32_16x16x32_bf16 v[188:191], v[28:31], v[100:103], v[188:191]
	v_mfma_f32_16x16x32_bf16 v[152:155], v[36:39], v[100:103], v[152:155]
	v_mfma_f32_16x16x32_bf16 v[176:179], v[28:31], v[108:111], v[176:179]
	v_mfma_f32_16x16x32_bf16 v[144:147], v[36:39], v[108:111], v[144:147]
	v_mfma_f32_16x16x32_bf16 v[168:171], v[28:31], v[116:119], v[168:171]
	v_mfma_f32_16x16x32_bf16 v[136:139], v[36:39], v[116:119], v[136:139]
	v_mfma_f32_16x16x32_bf16 v[192:195], v[32:35], v[96:99], v[192:195]
	v_mfma_f32_16x16x32_bf16 v[160:163], v[40:43], v[96:99], v[160:163]
	v_mfma_f32_16x16x32_bf16 v[188:191], v[32:35], v[104:107], v[188:191]
	v_mfma_f32_16x16x32_bf16 v[152:155], v[40:43], v[104:107], v[152:155]
	v_mfma_f32_16x16x32_bf16 v[176:179], v[32:35], v[112:115], v[176:179]
	v_mfma_f32_16x16x32_bf16 v[144:147], v[40:43], v[112:115], v[144:147]
	v_mfma_f32_16x16x32_bf16 v[168:171], v[32:35], v[120:123], v[168:171]
	v_mfma_f32_16x16x32_bf16 v[136:139], v[40:43], v[120:123], v[136:139]
	s_setprio 0
	s_setprio 1
	v_mfma_f32_16x16x32_bf16 v[180:183], v[44:47], v[92:95], v[180:183]
	v_mfma_f32_16x16x32_bf16 v[92:95], v[52:55], v[92:95], v[156:159]
	v_mfma_f32_16x16x32_bf16 v[180:183], v[48:51], v[96:99], v[180:183]
	v_mfma_f32_16x16x32_bf16 v[92:95], v[56:59], v[96:99], v[92:95]
	v_mfma_f32_16x16x32_bf16 v[96:99], v[44:47], v[100:103], v[184:187]
	v_mfma_f32_16x16x32_bf16 v[100:103], v[52:55], v[100:103], v[148:151]
	v_mfma_f32_16x16x32_bf16 v[96:99], v[48:51], v[104:107], v[96:99]
	v_mfma_f32_16x16x32_bf16 v[100:103], v[56:59], v[104:107], v[100:103]
	v_mfma_f32_16x16x32_bf16 v[104:107], v[44:47], v[108:111], v[172:175]
	v_mfma_f32_16x16x32_bf16 v[108:111], v[52:55], v[108:111], v[140:143]
	v_mfma_f32_16x16x32_bf16 v[104:107], v[48:51], v[112:115], v[104:107]
	v_mfma_f32_16x16x32_bf16 v[108:111], v[56:59], v[112:115], v[108:111]
	v_mfma_f32_16x16x32_bf16 v[112:115], v[44:47], v[116:119], v[164:167]
	v_mfma_f32_16x16x32_bf16 v[116:119], v[52:55], v[116:119], v[132:135]
	v_mfma_f32_16x16x32_bf16 v[112:115], v[48:51], v[120:123], v[112:115]
	v_mfma_f32_16x16x32_bf16 v[116:119], v[56:59], v[120:123], v[116:119]
	s_setprio 0
	s_barrier
	s_add_i32 s17, s17, s54
	v_lshl_add_u64 v[234:235], s[10:11], 0, v[226:227]
	s_mov_b32 m0, s17
	ds_read_b128 v[120:123], v216 offset:16384
	ds_read_b128 v[132:135], v216 offset:17408
	ds_read_b128 v[140:143], v216 offset:18432
	ds_read_b128 v[148:151], v216 offset:19456
	ds_read_b128 v[156:159], v216 offset:20480
	ds_read_b128 v[164:167], v216 offset:21504
	ds_read_b128 v[172:175], v216 offset:22528
	ds_read_b128 v[184:187], v216 offset:23552
	global_load_lds_dwordx4 v[234:235], off
	s_add_i32 m0, s17, 0x2000
	s_add_u32 s42, s10, 0x80000
	v_lshl_add_u64 v[236:237], s[10:11], 0, v[222:223]
	s_addc_u32 s43, s11, 0
	s_add_i32 s17, s41, s54
	global_load_lds_dwordx4 v[236:237], off
	v_lshl_add_u64 v[196:197], s[42:43], 0, v[226:227]
	s_mov_b32 m0, s17
	v_lshl_add_u64 v[238:239], s[14:15], 0, v[228:229]
	global_load_lds_dwordx4 v[196:197], off
	v_lshl_add_u64 v[196:197], s[42:43], 0, v[222:223]
	s_add_i32 m0, s17, 0x2000
	v_lshl_add_u64 v[240:241], s[14:15], 0, v[224:225]
	global_load_lds_dwordx4 v[196:197], off
	s_mov_b32 m0, s58
	s_nop 0
	global_load_lds_dwordx4 v[238:239], off
	s_mov_b32 m0, s59
	s_nop 0
	global_load_lds_dwordx4 v[240:241], off
	s_waitcnt vmcnt(8)
	s_waitcnt lgkmcnt(0)
	s_barrier
	s_setprio 1
	s_waitcnt lgkmcnt(0)
	v_mfma_f32_16x16x32_bf16 v[128:131], v[28:31], v[120:123], v[128:131]
	v_mfma_f32_16x16x32_bf16 v[64:67], v[36:39], v[120:123], v[64:67]
	v_mfma_f32_16x16x32_bf16 v[88:91], v[28:31], v[140:143], v[88:91]
	v_mfma_f32_16x16x32_bf16 v[24:27], v[36:39], v[140:143], v[24:27]
	v_mfma_f32_16x16x32_bf16 v[80:83], v[28:31], v[156:159], v[80:83]
	v_mfma_f32_16x16x32_bf16 v[16:19], v[36:39], v[156:159], v[16:19]
	v_mfma_f32_16x16x32_bf16 v[8:11], v[36:39], v[172:175], v[8:11]
	v_mfma_f32_16x16x32_bf16 v[128:131], v[32:35], v[132:135], v[128:131]
	v_mfma_f32_16x16x32_bf16 v[64:67], v[40:43], v[132:135], v[64:67]
	v_mfma_f32_16x16x32_bf16 v[88:91], v[32:35], v[148:151], v[88:91]
	v_mfma_f32_16x16x32_bf16 v[24:27], v[40:43], v[148:151], v[24:27]
	v_mfma_f32_16x16x32_bf16 v[80:83], v[32:35], v[164:167], v[80:83]
	v_mfma_f32_16x16x32_bf16 v[16:19], v[40:43], v[164:167], v[16:19]
	v_mfma_f32_16x16x32_bf16 v[28:31], v[28:31], v[172:175], v[72:75]
	v_mfma_f32_16x16x32_bf16 v[8:11], v[40:43], v[184:187], v[8:11]
	v_mfma_f32_16x16x32_bf16 v[28:31], v[32:35], v[184:187], v[28:31]
	s_setprio 0
	s_setprio 1
	v_mfma_f32_16x16x32_bf16 v[36:39], v[52:55], v[120:123], v[60:63]
	v_mfma_f32_16x16x32_bf16 v[20:23], v[52:55], v[140:143], v[20:23]
	v_mfma_f32_16x16x32_bf16 v[60:63], v[44:47], v[156:159], v[76:79]
	v_mfma_f32_16x16x32_bf16 v[12:15], v[52:55], v[156:159], v[12:15]
	v_mfma_f32_16x16x32_bf16 v[4:7], v[52:55], v[172:175], v[4:7]
	v_mfma_f32_16x16x32_bf16 v[32:35], v[44:47], v[120:123], v[124:127]
	v_mfma_f32_16x16x32_bf16 v[40:43], v[44:47], v[140:143], v[84:87]
	v_mfma_f32_16x16x32_bf16 v[20:23], v[56:59], v[148:151], v[20:23]
	v_mfma_f32_16x16x32_bf16 v[76:79], v[48:51], v[164:167], v[60:63]
	v_mfma_f32_16x16x32_bf16 v[12:15], v[56:59], v[164:167], v[12:15]
	v_mfma_f32_16x16x32_bf16 v[44:47], v[44:47], v[172:175], v[68:71]
	v_mfma_f32_16x16x32_bf16 v[4:7], v[56:59], v[184:187], v[4:7]
	v_mfma_f32_16x16x32_bf16 v[32:35], v[48:51], v[132:135], v[32:35]
	v_mfma_f32_16x16x32_bf16 v[36:39], v[56:59], v[132:135], v[36:39]
	v_mfma_f32_16x16x32_bf16 v[40:43], v[48:51], v[148:151], v[40:43]
	v_mfma_f32_16x16x32_bf16 v[44:47], v[48:51], v[184:187], v[44:47]
	s_setprio 0
	s_barrier
	s_add_i32 s17, 0, 0x18000
	v_add_u32_e32 v2, s17, v220
	s_add_i32 s41, 0, 0x1c000
	ds_read_b128 v[48:51], v2
	ds_read_b128 v[52:55], v2 offset:1024
	ds_read_b128 v[56:59], v2 offset:2048
	ds_read_b128 v[60:63], v2 offset:3072
	v_add_u32_e32 v2, s41, v220
	ds_read_b128 v[68:71], v2
	ds_read_b128 v[120:123], v2 offset:1024
	ds_read_b128 v[196:199], v2 offset:2048
	ds_read_b128 v[200:203], v2 offset:3072
	s_add_u32 s14, s14, 0x80000
	s_addc_u32 s15, s15, 0
	s_mov_b32 m0, s60
	v_lshl_add_u64 v[148:149], s[14:15], 0, v[228:229]
	ds_read_b128 v[72:75], v216 offset:32768
	ds_read_b128 v[84:87], v216 offset:33792
	ds_read_b128 v[124:127], v216 offset:34816
	ds_read_b128 v[132:135], v216 offset:35840
	ds_read_b128 v[140:143], v216 offset:36864
	ds_read_b128 v[164:167], v216 offset:37888
	ds_read_b128 v[204:207], v216 offset:38912
	ds_read_b128 v[208:211], v216 offset:39936
	global_load_lds_dwordx4 v[148:149], off
	v_lshl_add_u64 v[148:149], s[14:15], 0, v[224:225]
	s_mov_b32 m0, s61
	s_nop 0
	global_load_lds_dwordx4 v[148:149], off
	s_waitcnt vmcnt(8)
	s_waitcnt lgkmcnt(0)
	s_barrier
	s_setprio 1
	s_waitcnt lgkmcnt(0)
	v_mfma_f32_16x16x32_bf16 v[148:151], v[48:51], v[72:75], v[192:195]
	v_mfma_f32_16x16x32_bf16 v[192:195], v[52:55], v[84:87], v[148:151]
	v_mfma_f32_16x16x32_bf16 v[148:151], v[56:59], v[72:75], v[160:163]
	v_mfma_f32_16x16x32_bf16 v[160:163], v[60:63], v[84:87], v[148:151]
	v_mfma_f32_16x16x32_bf16 v[148:151], v[48:51], v[124:127], v[188:191]
	v_mfma_f32_16x16x32_bf16 v[188:191], v[52:55], v[132:135], v[148:151]
	v_mfma_f32_16x16x32_bf16 v[148:151], v[56:59], v[124:127], v[152:155]
	v_mfma_f32_16x16x32_bf16 v[152:155], v[60:63], v[132:135], v[148:151]
	v_mfma_f32_16x16x32_bf16 v[148:151], v[48:51], v[140:143], v[176:179]
	v_mfma_f32_16x16x32_bf16 v[176:179], v[52:55], v[164:167], v[148:151]
	v_mfma_f32_16x16x32_bf16 v[144:147], v[56:59], v[140:143], v[144:147]
	v_mfma_f32_16x16x32_bf16 v[148:151], v[48:51], v[204:207], v[168:171]
	v_mfma_f32_16x16x32_bf16 v[136:139], v[56:59], v[204:207], v[136:139]
	v_mfma_f32_16x16x32_bf16 v[144:147], v[60:63], v[164:167], v[144:147]
	v_mfma_f32_16x16x32_bf16 v[168:171], v[52:55], v[208:211], v[148:151]
	v_mfma_f32_16x16x32_bf16 v[136:139], v[60:63], v[208:211], v[136:139]
	s_setprio 0
	s_setprio 1
	v_mfma_f32_16x16x32_bf16 v[148:151], v[68:71], v[72:75], v[180:183]
	v_mfma_f32_16x16x32_bf16 v[72:75], v[196:199], v[72:75], v[92:95]
	v_mfma_f32_16x16x32_bf16 v[156:159], v[200:203], v[84:87], v[72:75]
	v_mfma_f32_16x16x32_bf16 v[72:75], v[68:71], v[124:127], v[96:99]
	v_mfma_f32_16x16x32_bf16 v[184:187], v[120:123], v[132:135], v[72:75]
	v_mfma_f32_16x16x32_bf16 v[72:75], v[196:199], v[124:127], v[100:103]
	v_mfma_f32_16x16x32_bf16 v[180:183], v[120:123], v[84:87], v[148:151]
	v_mfma_f32_16x16x32_bf16 v[148:151], v[200:203], v[132:135], v[72:75]
	v_mfma_f32_16x16x32_bf16 v[72:75], v[68:71], v[140:143], v[104:107]
	v_mfma_f32_16x16x32_bf16 v[172:175], v[120:123], v[164:167], v[72:75]
	v_mfma_f32_16x16x32_bf16 v[72:75], v[196:199], v[140:143], v[108:111]
	v_mfma_f32_16x16x32_bf16 v[140:143], v[200:203], v[164:167], v[72:75]
	v_mfma_f32_16x16x32_bf16 v[72:75], v[68:71], v[204:207], v[112:115]
	v_mfma_f32_16x16x32_bf16 v[164:167], v[120:123], v[208:211], v[72:75]
	v_mfma_f32_16x16x32_bf16 v[72:75], v[196:199], v[204:207], v[116:119]
	v_mfma_f32_16x16x32_bf16 v[132:135], v[200:203], v[208:211], v[72:75]
	s_setprio 0
	s_barrier
	s_add_i32 s14, s17, s54
	s_nop 3
	v_lshl_add_u64 v[72:73], v[234:235], 0, s[20:21]
	s_mov_b32 m0, s14
	ds_read_b128 v[84:87], v216 offset:49152
	ds_read_b128 v[92:95], v216 offset:50176
	ds_read_b128 v[96:99], v216 offset:51200
	ds_read_b128 v[100:103], v216 offset:52224
	ds_read_b128 v[104:107], v216 offset:53248
	ds_read_b128 v[108:111], v216 offset:54272
	ds_read_b128 v[112:115], v216 offset:55296
	ds_read_b128 v[116:119], v216 offset:56320
	global_load_lds_dwordx4 v[72:73], off
	s_add_i32 m0, s14, 0x2000
	s_add_u32 s10, s10, 0x80080
	v_lshl_add_u64 v[72:73], v[236:237], 0, s[20:21]
	s_addc_u32 s11, s11, 0
	s_add_i32 s14, s41, s54
	global_load_lds_dwordx4 v[72:73], off
	v_lshl_add_u64 v[72:73], s[10:11], 0, v[226:227]
	s_mov_b32 m0, s14
	s_nop 0
	global_load_lds_dwordx4 v[72:73], off
	v_lshl_add_u64 v[72:73], s[10:11], 0, v[222:223]
	s_add_i32 m0, s14, 0x2000
	s_nop 0
	global_load_lds_dwordx4 v[72:73], off
	v_lshl_add_u64 v[72:73], v[238:239], 0, s[20:21]
	s_mov_b32 m0, s65
	s_nop 0
	global_load_lds_dwordx4 v[72:73], off
	v_lshl_add_u64 v[72:73], v[240:241], 0, s[20:21]
	s_mov_b32 m0, s66
	s_nop 0
	global_load_lds_dwordx4 v[72:73], off
	s_add_i32 s16, s16, 2
	s_add_u32 s39, s39, 0x100
	s_addc_u32 s40, s40, 0
	s_add_u32 s8, s8, 0x100
	s_addc_u32 s9, s9, 0
	s_cmp_gt_u32 s16, 29
	s_waitcnt vmcnt(8)
	s_waitcnt lgkmcnt(0)
	s_barrier
	s_setprio 1
	s_waitcnt lgkmcnt(0)
	v_mfma_f32_16x16x32_bf16 v[72:75], v[48:51], v[84:87], v[128:131]
	v_mfma_f32_16x16x32_bf16 v[128:131], v[52:55], v[92:95], v[72:75]
	v_mfma_f32_16x16x32_bf16 v[72:75], v[48:51], v[96:99], v[88:91]
	v_mfma_f32_16x16x32_bf16 v[64:67], v[56:59], v[84:87], v[64:67]
	v_mfma_f32_16x16x32_bf16 v[88:91], v[52:55], v[100:103], v[72:75]
	v_mfma_f32_16x16x32_bf16 v[24:27], v[56:59], v[96:99], v[24:27]
	v_mfma_f32_16x16x32_bf16 v[72:75], v[48:51], v[104:107], v[80:83]
	v_mfma_f32_16x16x32_bf16 v[16:19], v[56:59], v[104:107], v[16:19]
	v_mfma_f32_16x16x32_bf16 v[28:31], v[48:51], v[112:115], v[28:31]
	v_mfma_f32_16x16x32_bf16 v[8:11], v[56:59], v[112:115], v[8:11]
	v_mfma_f32_16x16x32_bf16 v[64:67], v[60:63], v[92:95], v[64:67]
	v_mfma_f32_16x16x32_bf16 v[24:27], v[60:63], v[100:103], v[24:27]
	v_mfma_f32_16x16x32_bf16 v[80:83], v[52:55], v[108:111], v[72:75]
	v_mfma_f32_16x16x32_bf16 v[16:19], v[60:63], v[108:111], v[16:19]
	v_mfma_f32_16x16x32_bf16 v[72:75], v[52:55], v[116:119], v[28:31]
	v_mfma_f32_16x16x32_bf16 v[8:11], v[60:63], v[116:119], v[8:11]
	s_setprio 0
	s_setprio 1
	v_mfma_f32_16x16x32_bf16 v[28:31], v[68:71], v[84:87], v[32:35]
	v_mfma_f32_16x16x32_bf16 v[124:127], v[120:123], v[92:95], v[28:31]
	v_mfma_f32_16x16x32_bf16 v[28:31], v[196:199], v[84:87], v[36:39]
	v_mfma_f32_16x16x32_bf16 v[60:63], v[200:203], v[92:95], v[28:31]
	v_mfma_f32_16x16x32_bf16 v[28:31], v[68:71], v[96:99], v[40:43]
	v_mfma_f32_16x16x32_bf16 v[84:87], v[120:123], v[100:103], v[28:31]
	v_mfma_f32_16x16x32_bf16 v[28:31], v[68:71], v[104:107], v[76:79]
	v_mfma_f32_16x16x32_bf16 v[20:23], v[196:199], v[96:99], v[20:23]
	v_mfma_f32_16x16x32_bf16 v[76:79], v[120:123], v[108:111], v[28:31]
	v_mfma_f32_16x16x32_bf16 v[12:15], v[196:199], v[104:107], v[12:15]
	v_mfma_f32_16x16x32_bf16 v[28:31], v[68:71], v[112:115], v[44:47]
	v_mfma_f32_16x16x32_bf16 v[4:7], v[196:199], v[112:115], v[4:7]
	v_mfma_f32_16x16x32_bf16 v[20:23], v[200:203], v[100:103], v[20:23]
	v_mfma_f32_16x16x32_bf16 v[12:15], v[200:203], v[108:111], v[12:15]
	v_mfma_f32_16x16x32_bf16 v[68:71], v[120:123], v[116:119], v[28:31]
	v_mfma_f32_16x16x32_bf16 v[4:7], v[200:203], v[116:119], v[4:7]
	s_setprio 0
	s_barrier
	s_cbranch_scc0 .LBB0_1336
	v_readlane_b32 s8, v255, 6
	v_readlane_b32 s9, v255, 7
	s_and_b64 vcc, exec, s[8:9]
	s_mov_b32 s81, 0xb000
	s_cbranch_vccz .LBB0_1339
	s_barrier

.LBB0_1504:
	s_add_i32 s58, 0, 0x10000
	v_add_u32_e32 v2, s58, v216
	s_add_i32 s59, 0, 0x14000
	ds_read_b128 v[124:127], v2
	ds_read_b128 v[128:131], v2 offset:1024
	ds_read_b128 v[132:135], v2 offset:2048
	ds_read_b128 v[136:139], v2 offset:3072
	v_add_u32_e32 v2, s59, v216
	ds_read_b128 v[148:151], v2
	ds_read_b128 v[152:155], v2 offset:1024
	ds_read_b128 v[156:159], v2 offset:2048
	ds_read_b128 v[160:163], v2 offset:3072
	v_lshl_add_u64 v[208:209], s[22:23], 0, v[198:199]
	s_add_i32 m0, s31, 0xc000
	ds_read_b128 v[164:167], v217
	ds_read_b128 v[168:171], v217 offset:1024
	ds_read_b128 v[172:175], v217 offset:2048
	ds_read_b128 v[176:179], v217 offset:3072
	ds_read_b128 v[180:183], v217 offset:4096
	ds_read_b128 v[184:187], v217 offset:5120
	ds_read_b128 v[200:203], v217 offset:6144
	ds_read_b128 v[204:207], v217 offset:7168
	global_load_lds_dwordx4 v[208:209], off
	v_lshl_add_u64 v[208:209], s[22:23], 0, v[196:197]
	s_add_i32 m0, s31, 0xe000
	s_nop 0
	global_load_lds_dwordx4 v[208:209], off
	s_add_u32 s4, s22, 0x100
	s_addc_u32 s5, s23, 0
	s_cmpk_eq_i32 s57, 0x54
	s_cselect_b32 s27, s19, s5
	s_cselect_b32 s26, s18, s4
	s_cselect_b32 s25, s21, s56
	s_cselect_b32 s24, s20, s52
	s_waitcnt vmcnt(8)
	s_waitcnt lgkmcnt(0)
	s_barrier
	s_setprio 1
	s_waitcnt lgkmcnt(0)
	v_mfma_f32_16x16x32_bf16 v[144:147], v[124:127], v[164:167], v[144:147]
	v_mfma_f32_16x16x32_bf16 v[140:143], v[132:135], v[164:167], v[140:143]
	v_mfma_f32_16x16x32_bf16 v[112:115], v[124:127], v[172:175], v[112:115]
	v_mfma_f32_16x16x32_bf16 v[108:111], v[132:135], v[172:175], v[108:111]
	v_mfma_f32_16x16x32_bf16 v[96:99], v[124:127], v[180:183], v[96:99]
	v_mfma_f32_16x16x32_bf16 v[92:95], v[132:135], v[180:183], v[92:95]
	v_mfma_f32_16x16x32_bf16 v[80:83], v[124:127], v[200:203], v[80:83]
	v_mfma_f32_16x16x32_bf16 v[76:79], v[132:135], v[200:203], v[76:79]
	v_mfma_f32_16x16x32_bf16 v[144:147], v[128:131], v[168:171], v[144:147]
	v_mfma_f32_16x16x32_bf16 v[140:143], v[136:139], v[168:171], v[140:143]
	v_mfma_f32_16x16x32_bf16 v[112:115], v[128:131], v[176:179], v[112:115]
	v_mfma_f32_16x16x32_bf16 v[108:111], v[136:139], v[176:179], v[108:111]
	v_mfma_f32_16x16x32_bf16 v[96:99], v[128:131], v[184:187], v[96:99]
	v_mfma_f32_16x16x32_bf16 v[92:95], v[136:139], v[184:187], v[92:95]
	v_mfma_f32_16x16x32_bf16 v[80:83], v[128:131], v[204:207], v[80:83]
	v_mfma_f32_16x16x32_bf16 v[76:79], v[136:139], v[204:207], v[76:79]
	s_setprio 0
	s_setprio 1
	v_mfma_f32_16x16x32_bf16 v[120:123], v[148:151], v[164:167], v[120:123]
	v_mfma_f32_16x16x32_bf16 v[116:119], v[156:159], v[164:167], v[116:119]
	v_mfma_f32_16x16x32_bf16 v[104:107], v[148:151], v[172:175], v[104:107]
	v_mfma_f32_16x16x32_bf16 v[100:103], v[156:159], v[172:175], v[100:103]
	v_mfma_f32_16x16x32_bf16 v[88:91], v[148:151], v[180:183], v[88:91]
	v_mfma_f32_16x16x32_bf16 v[84:87], v[156:159], v[180:183], v[84:87]
	v_mfma_f32_16x16x32_bf16 v[72:75], v[148:151], v[200:203], v[72:75]
	v_mfma_f32_16x16x32_bf16 v[68:71], v[156:159], v[200:203], v[68:71]
	v_mfma_f32_16x16x32_bf16 v[120:123], v[152:155], v[168:171], v[120:123]
	v_mfma_f32_16x16x32_bf16 v[116:119], v[160:163], v[168:171], v[116:119]
	v_mfma_f32_16x16x32_bf16 v[104:107], v[152:155], v[176:179], v[104:107]
	v_mfma_f32_16x16x32_bf16 v[100:103], v[160:163], v[176:179], v[100:103]
	v_mfma_f32_16x16x32_bf16 v[88:91], v[152:155], v[184:187], v[88:91]
	v_mfma_f32_16x16x32_bf16 v[84:87], v[160:163], v[184:187], v[84:87]
	v_mfma_f32_16x16x32_bf16 v[72:75], v[152:155], v[204:207], v[72:75]
	v_mfma_f32_16x16x32_bf16 v[68:71], v[160:163], v[204:207], v[68:71]
	s_setprio 0
	s_barrier
	s_add_i32 s22, s58, s28
	v_lshl_add_u64 v[208:209], s[24:25], 0, v[192:193]
	s_mov_b32 m0, s22
	ds_read_b128 v[164:167], v217 offset:16384
	ds_read_b128 v[168:171], v217 offset:17408
	ds_read_b128 v[172:175], v217 offset:18432
	ds_read_b128 v[176:179], v217 offset:19456
	ds_read_b128 v[180:183], v217 offset:20480
	ds_read_b128 v[184:187], v217 offset:21504
	ds_read_b128 v[200:203], v217 offset:22528
	ds_read_b128 v[204:207], v217 offset:23552
	global_load_lds_dwordx4 v[208:209], off
	s_add_i32 m0, s22, 0x2000
	s_add_u32 s22, s24, 0x160000
	v_lshl_add_u64 v[210:211], s[24:25], 0, v[188:189]
	s_addc_u32 s23, s25, 0
	s_add_i32 s58, s59, s28
	global_load_lds_dwordx4 v[210:211], off
	v_lshl_add_u64 v[220:221], s[22:23], 0, v[192:193]
	s_mov_b32 m0, s58
	v_lshl_add_u64 v[222:223], s[26:27], 0, v[190:191]
	global_load_lds_dwordx4 v[220:221], off
	v_lshl_add_u64 v[220:221], s[22:23], 0, v[188:189]
	s_add_i32 m0, s58, 0x2000
	s_nop 0
	global_load_lds_dwordx4 v[220:221], off
	v_lshl_add_u64 v[220:221], s[26:27], 0, v[194:195]
	s_mov_b32 m0, s31
	s_nop 0
	global_load_lds_dwordx4 v[220:221], off
	s_mov_b32 m0, s34
	s_nop 0
	global_load_lds_dwordx4 v[222:223], off
	s_waitcnt vmcnt(8)
	s_waitcnt lgkmcnt(0)
	s_barrier
	s_setprio 1
	s_waitcnt lgkmcnt(0)
	v_mfma_f32_16x16x32_bf16 v[64:67], v[124:127], v[164:167], v[64:67]
	v_mfma_f32_16x16x32_bf16 v[60:63], v[132:135], v[164:167], v[60:63]
	v_mfma_f32_16x16x32_bf16 v[48:51], v[124:127], v[172:175], v[48:51]
	v_mfma_f32_16x16x32_bf16 v[44:47], v[132:135], v[172:175], v[44:47]
	v_mfma_f32_16x16x32_bf16 v[32:35], v[124:127], v[180:183], v[32:35]
	v_mfma_f32_16x16x32_bf16 v[28:31], v[132:135], v[180:183], v[28:31]
	v_mfma_f32_16x16x32_bf16 v[16:19], v[124:127], v[200:203], v[16:19]
	v_mfma_f32_16x16x32_bf16 v[12:15], v[132:135], v[200:203], v[12:15]
	v_mfma_f32_16x16x32_bf16 v[64:67], v[128:131], v[168:171], v[64:67]
	v_mfma_f32_16x16x32_bf16 v[60:63], v[136:139], v[168:171], v[60:63]
	v_mfma_f32_16x16x32_bf16 v[48:51], v[128:131], v[176:179], v[48:51]
	v_mfma_f32_16x16x32_bf16 v[44:47], v[136:139], v[176:179], v[44:47]
	v_mfma_f32_16x16x32_bf16 v[32:35], v[128:131], v[184:187], v[32:35]
	v_mfma_f32_16x16x32_bf16 v[28:31], v[136:139], v[184:187], v[28:31]
	v_mfma_f32_16x16x32_bf16 v[16:19], v[128:131], v[204:207], v[16:19]
	v_mfma_f32_16x16x32_bf16 v[12:15], v[136:139], v[204:207], v[12:15]
	s_setprio 0
	s_setprio 1
	v_mfma_f32_16x16x32_bf16 v[56:59], v[148:151], v[164:167], v[56:59]
	v_mfma_f32_16x16x32_bf16 v[52:55], v[156:159], v[164:167], v[52:55]
	v_mfma_f32_16x16x32_bf16 v[40:43], v[148:151], v[172:175], v[40:43]
	v_mfma_f32_16x16x32_bf16 v[36:39], v[156:159], v[172:175], v[36:39]
	v_mfma_f32_16x16x32_bf16 v[24:27], v[148:151], v[180:183], v[24:27]
	v_mfma_f32_16x16x32_bf16 v[20:23], v[156:159], v[180:183], v[20:23]
	v_mfma_f32_16x16x32_bf16 v[8:11], v[148:151], v[200:203], v[8:11]
	v_mfma_f32_16x16x32_bf16 v[4:7], v[156:159], v[200:203], v[4:7]
	v_mfma_f32_16x16x32_bf16 v[56:59], v[152:155], v[168:171], v[56:59]
	v_mfma_f32_16x16x32_bf16 v[52:55], v[160:163], v[168:171], v[52:55]
	v_mfma_f32_16x16x32_bf16 v[40:43], v[152:155], v[176:179], v[40:43]
	v_mfma_f32_16x16x32_bf16 v[36:39], v[160:163], v[176:179], v[36:39]
	v_mfma_f32_16x16x32_bf16 v[24:27], v[152:155], v[184:187], v[24:27]
	v_mfma_f32_16x16x32_bf16 v[20:23], v[160:163], v[184:187], v[20:23]
	v_mfma_f32_16x16x32_bf16 v[8:11], v[152:155], v[204:207], v[8:11]
	v_mfma_f32_16x16x32_bf16 v[4:7], v[160:163], v[204:207], v[4:7]
	s_setprio 0
	s_barrier
	s_add_i32 s58, 0, 0x18000
	v_add_u32_e32 v2, s58, v216
	s_add_i32 s59, 0, 0x1c000
	ds_read_b128 v[124:127], v2
	ds_read_b128 v[128:131], v2 offset:1024
	ds_read_b128 v[132:135], v2 offset:2048
	ds_read_b128 v[136:139], v2 offset:3072
	v_add_u32_e32 v2, s59, v216
	ds_read_b128 v[148:151], v2
	ds_read_b128 v[152:155], v2 offset:1024
	ds_read_b128 v[156:159], v2 offset:2048
	ds_read_b128 v[160:163], v2 offset:3072
	s_add_u32 s22, s26, 0x160000
	s_addc_u32 s23, s27, 0
	s_mov_b32 m0, s35
	v_lshl_add_u64 v[224:225], s[22:23], 0, v[194:195]
	ds_read_b128 v[164:167], v217 offset:32768
	ds_read_b128 v[168:171], v217 offset:33792
	ds_read_b128 v[172:175], v217 offset:34816
	ds_read_b128 v[176:179], v217 offset:35840
	ds_read_b128 v[180:183], v217 offset:36864
	ds_read_b128 v[184:187], v217 offset:37888
	ds_read_b128 v[200:203], v217 offset:38912
	ds_read_b128 v[204:207], v217 offset:39936
	global_load_lds_dwordx4 v[224:225], off
	v_lshl_add_u64 v[224:225], s[22:23], 0, v[190:191]
	s_mov_b32 m0, s36
	s_nop 0
	global_load_lds_dwordx4 v[224:225], off
	s_waitcnt vmcnt(8)
	s_waitcnt lgkmcnt(0)
	s_barrier
	s_setprio 1
	s_waitcnt lgkmcnt(0)
	v_mfma_f32_16x16x32_bf16 v[144:147], v[124:127], v[164:167], v[144:147]
	v_mfma_f32_16x16x32_bf16 v[140:143], v[132:135], v[164:167], v[140:143]
	v_mfma_f32_16x16x32_bf16 v[112:115], v[124:127], v[172:175], v[112:115]
	v_mfma_f32_16x16x32_bf16 v[108:111], v[132:135], v[172:175], v[108:111]
	v_mfma_f32_16x16x32_bf16 v[96:99], v[124:127], v[180:183], v[96:99]
	v_mfma_f32_16x16x32_bf16 v[92:95], v[132:135], v[180:183], v[92:95]
	v_mfma_f32_16x16x32_bf16 v[80:83], v[124:127], v[200:203], v[80:83]
	v_mfma_f32_16x16x32_bf16 v[76:79], v[132:135], v[200:203], v[76:79]
	v_mfma_f32_16x16x32_bf16 v[144:147], v[128:131], v[168:171], v[144:147]
	v_mfma_f32_16x16x32_bf16 v[140:143], v[136:139], v[168:171], v[140:143]
	v_mfma_f32_16x16x32_bf16 v[112:115], v[128:131], v[176:179], v[112:115]
	v_mfma_f32_16x16x32_bf16 v[108:111], v[136:139], v[176:179], v[108:111]
	v_mfma_f32_16x16x32_bf16 v[96:99], v[128:131], v[184:187], v[96:99]
	v_mfma_f32_16x16x32_bf16 v[92:95], v[136:139], v[184:187], v[92:95]
	v_mfma_f32_16x16x32_bf16 v[80:83], v[128:131], v[204:207], v[80:83]
	v_mfma_f32_16x16x32_bf16 v[76:79], v[136:139], v[204:207], v[76:79]
	s_setprio 0
	s_setprio 1
	v_mfma_f32_16x16x32_bf16 v[120:123], v[148:151], v[164:167], v[120:123]
	v_mfma_f32_16x16x32_bf16 v[116:119], v[156:159], v[164:167], v[116:119]
	v_mfma_f32_16x16x32_bf16 v[104:107], v[148:151], v[172:175], v[104:107]
	v_mfma_f32_16x16x32_bf16 v[100:103], v[156:159], v[172:175], v[100:103]
	v_mfma_f32_16x16x32_bf16 v[88:91], v[148:151], v[180:183], v[88:91]
	v_mfma_f32_16x16x32_bf16 v[84:87], v[156:159], v[180:183], v[84:87]
	v_mfma_f32_16x16x32_bf16 v[72:75], v[148:151], v[200:203], v[72:75]
	v_mfma_f32_16x16x32_bf16 v[68:71], v[156:159], v[200:203], v[68:71]
	v_mfma_f32_16x16x32_bf16 v[120:123], v[152:155], v[168:171], v[120:123]
	v_mfma_f32_16x16x32_bf16 v[116:119], v[160:163], v[168:171], v[116:119]
	v_mfma_f32_16x16x32_bf16 v[104:107], v[152:155], v[176:179], v[104:107]
	v_mfma_f32_16x16x32_bf16 v[100:103], v[160:163], v[176:179], v[100:103]
	v_mfma_f32_16x16x32_bf16 v[88:91], v[152:155], v[184:187], v[88:91]
	v_mfma_f32_16x16x32_bf16 v[84:87], v[160:163], v[184:187], v[84:87]
	v_mfma_f32_16x16x32_bf16 v[72:75], v[152:155], v[204:207], v[72:75]
	v_mfma_f32_16x16x32_bf16 v[68:71], v[160:163], v[204:207], v[68:71]
	s_setprio 0
	s_barrier
	s_add_i32 s22, s58, s28
	v_lshl_add_u64 v[208:209], v[208:209], 0, s[76:77]
	s_mov_b32 m0, s22
	ds_read_b128 v[164:167], v217 offset:49152
	ds_read_b128 v[168:171], v217 offset:50176
	ds_read_b128 v[172:175], v217 offset:51200
	ds_read_b128 v[176:179], v217 offset:52224
	ds_read_b128 v[180:183], v217 offset:53248
	ds_read_b128 v[184:187], v217 offset:54272
	ds_read_b128 v[200:203], v217 offset:55296
	ds_read_b128 v[204:207], v217 offset:56320
	global_load_lds_dwordx4 v[208:209], off
	s_add_i32 m0, s22, 0x2000
	s_add_u32 s22, s24, 0x160080
	v_lshl_add_u64 v[208:209], v[210:211], 0, s[76:77]
	s_addc_u32 s23, s25, 0
	s_add_i32 s24, s59, s28
	global_load_lds_dwordx4 v[208:209], off
	v_lshl_add_u64 v[208:209], s[22:23], 0, v[192:193]
	s_mov_b32 m0, s24
	s_nop 0
	global_load_lds_dwordx4 v[208:209], off
	v_lshl_add_u64 v[208:209], s[22:23], 0, v[188:189]
	s_add_i32 m0, s24, 0x2000
	s_nop 0
	global_load_lds_dwordx4 v[208:209], off
	v_lshl_add_u64 v[208:209], v[220:221], 0, s[76:77]
	s_mov_b32 m0, s40
	s_nop 0
	global_load_lds_dwordx4 v[208:209], off
	v_lshl_add_u64 v[208:209], v[222:223], 0, s[76:77]
	s_mov_b32 m0, s41
	s_nop 0
	global_load_lds_dwordx4 v[208:209], off
	s_add_i32 s57, s57, 2
	s_add_u32 s52, s52, 0x100
	s_addc_u32 s56, s56, 0
	s_cmpk_gt_u32 s57, 0x55
	s_mov_b64 s[22:23], s[4:5]
	s_waitcnt vmcnt(8)
	s_waitcnt lgkmcnt(0)
	s_barrier
	s_setprio 1
	s_waitcnt lgkmcnt(0)
	v_mfma_f32_16x16x32_bf16 v[64:67], v[124:127], v[164:167], v[64:67]
	v_mfma_f32_16x16x32_bf16 v[60:63], v[132:135], v[164:167], v[60:63]
	v_mfma_f32_16x16x32_bf16 v[48:51], v[124:127], v[172:175], v[48:51]
	v_mfma_f32_16x16x32_bf16 v[44:47], v[132:135], v[172:175], v[44:47]
	v_mfma_f32_16x16x32_bf16 v[32:35], v[124:127], v[180:183], v[32:35]
	v_mfma_f32_16x16x32_bf16 v[28:31], v[132:135], v[180:183], v[28:31]
	v_mfma_f32_16x16x32_bf16 v[16:19], v[124:127], v[200:203], v[16:19]
	v_mfma_f32_16x16x32_bf16 v[12:15], v[132:135], v[200:203], v[12:15]
	v_mfma_f32_16x16x32_bf16 v[64:67], v[128:131], v[168:171], v[64:67]
	v_mfma_f32_16x16x32_bf16 v[60:63], v[136:139], v[168:171], v[60:63]
	v_mfma_f32_16x16x32_bf16 v[48:51], v[128:131], v[176:179], v[48:51]
	v_mfma_f32_16x16x32_bf16 v[44:47], v[136:139], v[176:179], v[44:47]
	v_mfma_f32_16x16x32_bf16 v[32:35], v[128:131], v[184:187], v[32:35]
	v_mfma_f32_16x16x32_bf16 v[28:31], v[136:139], v[184:187], v[28:31]
	v_mfma_f32_16x16x32_bf16 v[16:19], v[128:131], v[204:207], v[16:19]
	v_mfma_f32_16x16x32_bf16 v[12:15], v[136:139], v[204:207], v[12:15]
	s_setprio 0
	s_setprio 1
	v_mfma_f32_16x16x32_bf16 v[56:59], v[148:151], v[164:167], v[56:59]
	v_mfma_f32_16x16x32_bf16 v[52:55], v[156:159], v[164:167], v[52:55]
	v_mfma_f32_16x16x32_bf16 v[40:43], v[148:151], v[172:175], v[40:43]
	v_mfma_f32_16x16x32_bf16 v[36:39], v[156:159], v[172:175], v[36:39]
	v_mfma_f32_16x16x32_bf16 v[24:27], v[148:151], v[180:183], v[24:27]
	v_mfma_f32_16x16x32_bf16 v[20:23], v[156:159], v[180:183], v[20:23]
	v_mfma_f32_16x16x32_bf16 v[8:11], v[148:151], v[200:203], v[8:11]
	v_mfma_f32_16x16x32_bf16 v[4:7], v[156:159], v[200:203], v[4:7]
	v_mfma_f32_16x16x32_bf16 v[56:59], v[152:155], v[168:171], v[56:59]
	v_mfma_f32_16x16x32_bf16 v[52:55], v[160:163], v[168:171], v[52:55]
	v_mfma_f32_16x16x32_bf16 v[40:43], v[152:155], v[176:179], v[40:43]
	v_mfma_f32_16x16x32_bf16 v[36:39], v[160:163], v[176:179], v[36:39]
	v_mfma_f32_16x16x32_bf16 v[24:27], v[152:155], v[184:187], v[24:27]
	v_mfma_f32_16x16x32_bf16 v[20:23], v[160:163], v[184:187], v[20:23]
	v_mfma_f32_16x16x32_bf16 v[8:11], v[152:155], v[204:207], v[8:11]
	v_mfma_f32_16x16x32_bf16 v[4:7], v[160:163], v[204:207], v[4:7]
	s_setprio 0
	s_barrier
	s_cbranch_scc0 .LBB0_1504
	s_and_b64 vcc, exec, s[16:17]
	s_cbranch_vccz .LBB0_1507
	s_barrier
